# context-attention item: the next key/value chunk's loads issued before the current chunk's scores and softmax (were issued after them), into v208-223
# speedup vs baseline: 1.0033x; 1.0022x over previous
.LBB0_364:
	v_add3_u32 v11, s39, v136, v128
	v_cvt_pk_bf16_f32 v8, v64, v65
	v_add_u32_e32 v64, 0x2000, v11
	ds_read2_b64 v[12:15], v64 offset0:128 offset1:130
	v_cvt_pk_bf16_f32 v0, v66, v67
	v_cvt_pk_bf16_f32 v1, v70, v71
	v_cvt_pk_bf16_f32 v2, v74, v83
	v_cvt_pk_bf16_f32 v3, v86, v87
	v_add_u32_e32 v65, 0x3000, v11
	v_cvt_pk_bf16_f32 v4, v88, v89
	s_waitcnt lgkmcnt(0)
	v_mfma_f32_32x32x16_bf16 v[32:47], v[12:15], v[0:3], v[32:47]
	ds_read2_b64 v[12:15], v65 offset0:192 offset1:194
	v_cvt_pk_bf16_f32 v5, v90, v91
	v_cvt_pk_bf16_f32 v6, v92, v93
	v_cvt_pk_bf16_f32 v7, v94, v95
	v_cvt_pk_bf16_f32 v9, v68, v69
	v_cvt_pk_bf16_f32 v10, v72, v85
	v_cvt_pk_bf16_f32 v11, v76, v73
	s_waitcnt lgkmcnt(0)
	v_mfma_f32_32x32x16_bf16 v[16:31], v[12:15], v[0:3], v[16:31]
	ds_read2_b64 v[0:3], v64 offset0:132 offset1:134
	ds_read2_b64 v[12:15], v64 offset0:140 offset1:142
	s_bitcmp1_b32 s18, 0
	s_cselect_b32 s0, 0x4800, 0
	s_add_i32 s18, s18, 1
	s_add_i32 s38, s38, 2
	v_add_f32_e32 v169, v112, v169
	s_waitcnt lgkmcnt(1)
	v_mfma_f32_32x32x16_bf16 v[32:47], v[0:3], v[4:7], v[32:47]
	ds_read2_b64 v[0:3], v65 offset0:196 offset1:198
	v_lshl_add_u64 v[116:117], v[116:117], 0, s[46:47]
	v_lshl_add_u64 v[118:119], v[118:119], 0, s[46:47]
	v_lshl_add_u64 v[120:121], v[120:121], 0, s[10:11]
	s_cmp_eq_u32 s18, 4
	v_lshl_add_u64 v[122:123], v[122:123], 0, s[10:11]
	s_waitcnt lgkmcnt(0)
	v_mfma_f32_32x32x16_bf16 v[16:31], v[0:3], v[4:7], v[16:31]
	ds_read2_b64 v[0:3], v64 offset0:136 offset1:138
	v_cvt_pk_bf16_f32 v4, v78, v75
	v_cvt_pk_bf16_f32 v5, v80, v77
	v_cvt_pk_bf16_f32 v6, v82, v79
	v_cvt_pk_bf16_f32 v7, v84, v81
	s_waitcnt lgkmcnt(0)
	v_mfma_f32_32x32x16_bf16 v[32:47], v[0:3], v[8:11], v[32:47]
	ds_read2_b64 v[0:3], v65 offset0:200 offset1:202
	s_waitcnt lgkmcnt(0)
	v_mfma_f32_32x32x16_bf16 v[16:31], v[0:3], v[8:11], v[16:31]
	ds_read2_b64 v[0:3], v65 offset0:204 offset1:206
	v_lshlrev_b32_e32 v8, 1, v115
	v_lshlrev_b32_e32 v9, 1, v126
	v_add3_u32 v8, s0, v8, v114
	v_add3_u32 v9, s0, v9, v114
	s_waitcnt vmcnt(3)
	ds_write_b128 v8, v[208:211]
	s_waitcnt vmcnt(2)
	ds_write_b128 v8, v[212:215] offset:9216
	s_waitcnt vmcnt(1)
	ds_write_b128 v9, v[216:219]
	s_waitcnt vmcnt(0)
	ds_write_b128 v9, v[220:223] offset:9216
	v_mfma_f32_32x32x16_bf16 v[32:47], v[12:15], v[4:7], v[32:47]
	s_waitcnt lgkmcnt(0)
	s_barrier
	v_mfma_f32_32x32x16_bf16 v[16:31], v[0:3], v[4:7], v[16:31]
	s_cbranch_scc1 .LBB0_369
.LBB0_365:
	v_lshl_add_u64 v[224:225], v[118:119], 0, v[134:135]
	v_lshl_add_u64 v[226:227], v[120:121], 0, v[134:135]
	v_lshl_add_u64 v[228:229], v[116:117], 0, v[134:135]
	v_lshl_add_u64 v[230:231], v[122:123], 0, v[134:135]
	global_load_dwordx4 v[208:211], v[224:225], off
	global_load_dwordx4 v[212:215], v[226:227], off
	global_load_dwordx4 v[216:219], v[228:229], off
	global_load_dwordx4 v[220:223], v[230:231], off
	s_and_b32 s39, s38, 2
	s_mulk_i32 s39, 0x2400
	v_lshlrev_b32_e32 v128, 1, v168
	v_add3_u32 v68, s39, v128, v127
	ds_read_b128 v[0:3], v68
	ds_read_b128 v[4:7], v68 offset:32
	s_andn2_b64 vcc, exec, s[12:13]
	s_waitcnt lgkmcnt(1)
	v_mfma_f32_32x32x16_bf16 v[48:63], v[0:3], v[108:111], 0
	ds_read_b128 v[0:3], v68 offset:64
	ds_read_b128 v[64:67], v68 offset:4640
	s_waitcnt lgkmcnt(2)
	v_mfma_f32_32x32x16_bf16 v[48:63], v[4:7], v[104:107], v[48:63]
	s_waitcnt lgkmcnt(1)
	v_mfma_f32_32x32x16_bf16 v[48:63], v[0:3], v[100:103], v[48:63]
	ds_read_b128 v[0:3], v68 offset:96
	s_waitcnt lgkmcnt(0)
	v_mfma_f32_32x32x16_bf16 v[48:63], v[0:3], v[96:99], v[48:63]
	ds_read_b128 v[0:3], v68 offset:4608
	s_waitcnt lgkmcnt(0)
	v_mfma_f32_32x32x16_bf16 v[0:15], v[0:3], v[108:111], 0
	v_mfma_f32_32x32x16_bf16 v[0:15], v[64:67], v[104:107], v[0:15]
	ds_read_b128 v[64:67], v68 offset:4672
	s_waitcnt lgkmcnt(0)
	v_mfma_f32_32x32x16_bf16 v[0:15], v[64:67], v[100:103], v[0:15]
	ds_read_b128 v[64:67], v68 offset:4704
	s_waitcnt lgkmcnt(0)
	v_mfma_f32_32x32x16_bf16 v[0:15], v[64:67], v[96:99], v[0:15]
	s_cbranch_vccnz .LBB0_367
	s_nop 0
	v_sub_f32_e32 v48, v48, v113
	v_sub_f32_e32 v49, v49, v113
	v_sub_f32_e32 v50, v50, v113
	v_sub_f32_e32 v51, v51, v113
	v_sub_f32_e32 v52, v52, v113
	v_sub_f32_e32 v53, v53, v113
	v_sub_f32_e32 v54, v54, v113
	v_sub_f32_e32 v55, v55, v113
	v_sub_f32_e32 v56, v56, v113
	v_sub_f32_e32 v57, v57, v113
	v_sub_f32_e32 v58, v58, v113
	v_sub_f32_e32 v59, v59, v113
	v_sub_f32_e32 v60, v60, v113
	v_sub_f32_e32 v61, v61, v113
	v_sub_f32_e32 v62, v62, v113
	v_sub_f32_e32 v63, v63, v113
	v_sub_f32_e32 v0, v0, v113
	v_sub_f32_e32 v1, v1, v113
	v_sub_f32_e32 v2, v2, v113
	v_sub_f32_e32 v3, v3, v113
	v_sub_f32_e32 v4, v4, v113
	v_sub_f32_e32 v5, v5, v113
	v_sub_f32_e32 v6, v6, v113
	v_sub_f32_e32 v7, v7, v113
	v_sub_f32_e32 v8, v8, v113
	v_sub_f32_e32 v9, v9, v113
	v_sub_f32_e32 v10, v10, v113
	v_sub_f32_e32 v11, v11, v113
	v_sub_f32_e32 v12, v12, v113
	v_sub_f32_e32 v13, v13, v113
	v_sub_f32_e32 v14, v14, v113
	v_sub_f32_e32 v15, v15, v113
